# RES epilogue: second-half XB loads hoisted to the epilogue start (dead temps), single vmcnt instead of the 8-step ladder behind the stores
# speedup vs baseline: 1.0081x; 1.0081x over previous
.LBB0_1347:
	v_lshl_add_u32 v182, s46, 8, v196
	v_lshl_or_b32 v180, s45, 8, v198
	v_readlane_b32 s6, v254, 28
	v_ashrrev_i32_e32 v181, 31, v180
	v_readlane_b32 s7, v254, 29
	v_ashrrev_i32_e32 v183, 31, v182
	v_lshlrev_b64 v[122:123], 11, v[182:183]
	v_lshl_add_u64 v[178:179], v[180:181], 1, s[6:7]
	v_or_b32_e32 v188, 16, v182
	v_lshl_add_u64 v[122:123], v[178:179], 0, v[122:123]
	v_ashrrev_i32_e32 v189, 31, v188
	global_load_dwordx4 v[200:203], v[122:123], off
	global_load_dwordx4 v[154:157], v[122:123], off offset:256
	v_lshlrev_b64 v[122:123], 11, v[188:189]
	v_or_b32_e32 v186, 32, v182
	v_lshl_add_u64 v[122:123], v[178:179], 0, v[122:123]
	v_ashrrev_i32_e32 v187, 31, v186
	global_load_dwordx4 v[150:153], v[122:123], off
	global_load_dwordx4 v[146:149], v[122:123], off offset:256
	v_lshlrev_b64 v[122:123], 11, v[186:187]
	v_or_b32_e32 v184, 48, v182
	v_lshl_add_u64 v[122:123], v[178:179], 0, v[122:123]
	v_ashrrev_i32_e32 v185, 31, v184
	global_load_dwordx4 v[142:145], v[122:123], off
	global_load_dwordx4 v[138:141], v[122:123], off offset:256
	v_lshlrev_b64 v[122:123], 11, v[184:185]
	v_lshl_add_u64 v[122:123], v[178:179], 0, v[122:123]
	global_load_dwordx4 v[134:137], v[122:123], off
	s_nop 0
	global_load_dwordx4 v[122:125], v[122:123], off offset:256
	v_lshlrev_b64 v[192:193], 10, v[182:183]
	v_lshl_add_u64 v[190:191], v[192:193], 0, v[180:181]
	s_andn2_b64 vcc, exec, s[18:19]
	v_lshl_add_u64 v[194:195], v[190:191], 2, s[2:3]
	v_add_u32_e32 v168, 0x80, v182
	v_ashrrev_i32_e32 v169, 31, v168
	v_lshlrev_b64 v[168:169], 11, v[168:169]
	v_lshl_add_u64 v[168:169], v[178:179], 0, v[168:169]
	global_load_dwordx4 v[204:207], v[168:169], off
	global_load_dwordx4 v[214:217], v[168:169], off offset:256
	v_add_u32_e32 v168, 0x90, v182
	v_ashrrev_i32_e32 v169, 31, v168
	v_lshlrev_b64 v[168:169], 11, v[168:169]
	v_lshl_add_u64 v[168:169], v[178:179], 0, v[168:169]
	global_load_dwordx4 v[224:227], v[168:169], off
	global_load_dwordx4 v[228:231], v[168:169], off offset:256
	v_add_u32_e32 v168, 0xa0, v182
	v_ashrrev_i32_e32 v169, 31, v168
	v_lshlrev_b64 v[168:169], 11, v[168:169]
	v_lshl_add_u64 v[168:169], v[178:179], 0, v[168:169]
	global_load_dwordx4 v[232:235], v[168:169], off
	global_load_dwordx4 v[236:239], v[168:169], off offset:256
	v_add_u32_e32 v168, 0xb0, v182
	v_ashrrev_i32_e32 v169, 31, v168
	v_lshlrev_b64 v[168:169], 11, v[168:169]
	v_lshl_add_u64 v[168:169], v[178:179], 0, v[168:169]
	global_load_dwordx4 v[248:251], v[168:169], off
	global_load_dwordx2 v[208:209], v[168:169], off offset:256
	global_load_dwordx2 v[164:165], v[168:169], off offset:264
	s_waitcnt vmcnt(9)
	v_lshlrev_b32_e32 v162, 16, v200
	v_and_b32_e32 v163, 0xffff0000, v200
	v_pk_fma_f32 v[130:131], v[158:159], v[130:131], v[162:163]
	v_lshlrev_b32_e32 v162, 16, v201
	v_and_b32_e32 v163, 0xffff0000, v201
	v_pk_fma_f32 v[132:133], v[158:159], v[132:133], v[162:163]
	v_lshlrev_b32_e32 v162, 16, v202
	v_and_b32_e32 v163, 0xffff0000, v202
	v_pk_fma_f32 v[126:127], v[158:159], v[126:127], v[162:163]
	v_lshlrev_b32_e32 v162, 16, v203
	v_and_b32_e32 v163, 0xffff0000, v203
	v_pk_fma_f32 v[128:129], v[158:159], v[128:129], v[162:163]
	v_cndmask_b32_e64 v162, 0, 1, s[18:19]
	v_cmp_ne_u32_e64 s[6:7], 1, v162
	s_cbranch_vccnz .LBB0_1414
	global_store_dwordx4 v[194:195], v[130:133], off
	global_store_dwordx4 v[194:195], v[126:129], off offset:16
	s_cbranch_execnz .LBB0_1350

.LBB0_1379:
	s_or_b64 exec, exec, s[26:27]
	v_add_u32_e32 v100, 0x80, v182
	v_ashrrev_i32_e32 v101, 31, v100
	s_waitcnt lgkmcnt(0)
	v_lshlrev_b64 v[66:67], 11, v[100:101]
	v_add_u32_e32 v98, 0x90, v182
	v_lshl_add_u64 v[66:67], v[178:179], 0, v[66:67]
	v_ashrrev_i32_e32 v99, 31, v98
	s_waitcnt vmcnt(12)
	v_mov_b64_e32 v[106:107], v[204:205]
	v_mov_b64_e32 v[108:109], v[206:207]
	v_mov_b64_e32 v[90:91], v[214:215]
	v_mov_b64_e32 v[92:93], v[216:217]
	v_lshlrev_b64 v[66:67], 11, v[98:99]
	v_add_u32_e32 v96, 0xa0, v182
	v_lshl_add_u64 v[66:67], v[178:179], 0, v[66:67]
	v_ashrrev_i32_e32 v97, 31, v96
	v_mov_b64_e32 v[86:87], v[224:225]
	v_mov_b64_e32 v[88:89], v[226:227]
	v_mov_b64_e32 v[82:83], v[228:229]
	v_mov_b64_e32 v[84:85], v[230:231]
	v_lshlrev_b64 v[66:67], 11, v[96:97]
	v_add_u32_e32 v94, 0xb0, v182
	v_lshl_add_u64 v[66:67], v[178:179], 0, v[66:67]
	v_ashrrev_i32_e32 v95, 31, v94
	v_mov_b64_e32 v[78:79], v[232:233]
	v_mov_b64_e32 v[80:81], v[234:235]
	v_mov_b64_e32 v[74:75], v[236:237]
	v_mov_b64_e32 v[76:77], v[238:239]
	v_lshlrev_b64 v[66:67], 11, v[94:95]
	v_lshl_add_u64 v[66:67], v[178:179], 0, v[66:67]
	v_mov_b64_e32 v[70:71], v[248:249]
	v_mov_b64_e32 v[72:73], v[250:251]
	s_nop 0
	v_mov_b64_e32 v[66:67], v[208:209]
	v_mov_b64_e32 v[68:69], v[164:165]
	v_lshlrev_b64 v[104:105], 10, v[100:101]
	v_lshl_add_u64 v[102:103], v[104:105], 0, v[180:181]
	s_and_b64 vcc, exec, s[6:7]
	v_lshlrev_b32_e32 v110, 16, v106
	v_and_b32_e32 v111, 0xffff0000, v106
	v_lshlrev_b32_e32 v106, 16, v107
	v_and_b32_e32 v107, 0xffff0000, v107
	v_pk_fma_f32 v[64:65], v[158:159], v[64:65], v[106:107]
	v_lshlrev_b32_e32 v106, 16, v108
	v_and_b32_e32 v107, 0xffff0000, v108
	v_pk_fma_f32 v[58:59], v[158:159], v[58:59], v[106:107]
	v_lshlrev_b32_e32 v106, 16, v109
	v_and_b32_e32 v107, 0xffff0000, v109
	v_pk_fma_f32 v[62:63], v[158:159], v[62:63], v[110:111]
	v_pk_fma_f32 v[60:61], v[158:159], v[60:61], v[106:107]
	v_lshl_add_u64 v[106:107], v[102:103], 2, s[2:3]
	s_cbranch_vccnz .LBB0_1422
	global_store_dwordx4 v[106:107], v[62:65], off
	global_store_dwordx4 v[106:107], v[58:61], off offset:16
	s_cbranch_execnz .LBB0_1382

.LBB0_1382:
	v_lshlrev_b32_e32 v104, 16, v90
	v_and_b32_e32 v105, 0xffff0000, v90
	v_lshlrev_b32_e32 v90, 16, v91
	v_and_b32_e32 v91, 0xffff0000, v91
	v_pk_fma_f32 v[56:57], v[158:159], v[56:57], v[90:91]
	v_lshlrev_b32_e32 v90, 16, v92
	v_and_b32_e32 v91, 0xffff0000, v92
	v_pk_fma_f32 v[50:51], v[158:159], v[50:51], v[90:91]
	v_lshlrev_b32_e32 v90, 16, v93
	v_and_b32_e32 v91, 0xffff0000, v93
	v_pk_fma_f32 v[54:55], v[158:159], v[54:55], v[104:105]
	s_and_b64 vcc, exec, s[6:7]
	v_pk_fma_f32 v[52:53], v[158:159], v[52:53], v[90:91]
	s_cbranch_vccnz .LBB0_1423
	global_store_dwordx4 v[106:107], v[54:57], off offset:512
	global_store_dwordx4 v[106:107], v[50:53], off offset:528
	s_cbranch_execnz .LBB0_1385

.LBB0_1387:
	s_or_b64 exec, exec, s[26:27]
	v_lshlrev_b32_e32 v52, 16, v86
	v_and_b32_e32 v53, 0xffff0000, v86
	v_pk_fma_f32 v[46:47], v[158:159], v[46:47], v[52:53]
	v_lshlrev_b32_e32 v52, 16, v87
	v_and_b32_e32 v53, 0xffff0000, v87
	v_lshlrev_b64 v[54:55], 10, v[98:99]
	v_pk_fma_f32 v[48:49], v[158:159], v[48:49], v[52:53]
	v_lshlrev_b32_e32 v52, 16, v88
	v_and_b32_e32 v53, 0xffff0000, v88
	s_waitcnt lgkmcnt(0)
	v_lshl_add_u64 v[50:51], v[54:55], 0, v[180:181]
	v_pk_fma_f32 v[42:43], v[158:159], v[42:43], v[52:53]
	v_lshlrev_b32_e32 v52, 16, v89
	v_and_b32_e32 v53, 0xffff0000, v89
	v_pk_fma_f32 v[44:45], v[158:159], v[44:45], v[52:53]
	s_and_b64 vcc, exec, s[6:7]
	v_lshl_add_u64 v[52:53], v[50:51], 2, s[2:3]
	s_cbranch_vccnz .LBB0_1424
	global_store_dwordx4 v[52:53], v[46:49], off
	global_store_dwordx4 v[52:53], v[42:45], off offset:16
	s_cbranch_execnz .LBB0_1390

.LBB0_1390:
	v_lshlrev_b32_e32 v54, 16, v82
	v_and_b32_e32 v55, 0xffff0000, v82
	v_pk_fma_f32 v[38:39], v[158:159], v[38:39], v[54:55]
	v_lshlrev_b32_e32 v54, 16, v83
	v_and_b32_e32 v55, 0xffff0000, v83
	v_pk_fma_f32 v[40:41], v[158:159], v[40:41], v[54:55]
	v_lshlrev_b32_e32 v54, 16, v84
	v_and_b32_e32 v55, 0xffff0000, v84
	v_pk_fma_f32 v[34:35], v[158:159], v[34:35], v[54:55]
	v_lshlrev_b32_e32 v54, 16, v85
	v_and_b32_e32 v55, 0xffff0000, v85
	s_and_b64 vcc, exec, s[6:7]
	v_pk_fma_f32 v[36:37], v[158:159], v[36:37], v[54:55]
	s_cbranch_vccnz .LBB0_1425
	global_store_dwordx4 v[52:53], v[38:41], off offset:512
	global_store_dwordx4 v[52:53], v[34:37], off offset:528
	s_cbranch_execnz .LBB0_1393

.LBB0_1395:
	s_or_b64 exec, exec, s[26:27]
	v_lshlrev_b32_e32 v36, 16, v78
	v_and_b32_e32 v37, 0xffff0000, v78
	v_pk_fma_f32 v[30:31], v[158:159], v[30:31], v[36:37]
	v_lshlrev_b32_e32 v36, 16, v79
	v_and_b32_e32 v37, 0xffff0000, v79
	v_lshlrev_b64 v[38:39], 10, v[96:97]
	v_pk_fma_f32 v[32:33], v[158:159], v[32:33], v[36:37]
	v_lshlrev_b32_e32 v36, 16, v80
	v_and_b32_e32 v37, 0xffff0000, v80
	s_waitcnt lgkmcnt(0)
	v_lshl_add_u64 v[34:35], v[38:39], 0, v[180:181]
	v_pk_fma_f32 v[26:27], v[158:159], v[26:27], v[36:37]
	v_lshlrev_b32_e32 v36, 16, v81
	v_and_b32_e32 v37, 0xffff0000, v81
	v_pk_fma_f32 v[28:29], v[158:159], v[28:29], v[36:37]
	s_and_b64 vcc, exec, s[6:7]
	v_lshl_add_u64 v[36:37], v[34:35], 2, s[2:3]
	s_cbranch_vccnz .LBB0_1426
	global_store_dwordx4 v[36:37], v[30:33], off
	global_store_dwordx4 v[36:37], v[26:29], off offset:16
	s_cbranch_execnz .LBB0_1398

.LBB0_1398:
	v_lshlrev_b32_e32 v38, 16, v74
	v_and_b32_e32 v39, 0xffff0000, v74
	v_pk_fma_f32 v[22:23], v[158:159], v[22:23], v[38:39]
	v_lshlrev_b32_e32 v38, 16, v75
	v_and_b32_e32 v39, 0xffff0000, v75
	v_pk_fma_f32 v[24:25], v[158:159], v[24:25], v[38:39]
	v_lshlrev_b32_e32 v38, 16, v76
	v_and_b32_e32 v39, 0xffff0000, v76
	v_pk_fma_f32 v[18:19], v[158:159], v[18:19], v[38:39]
	v_lshlrev_b32_e32 v38, 16, v77
	v_and_b32_e32 v39, 0xffff0000, v77
	s_and_b64 vcc, exec, s[6:7]
	v_pk_fma_f32 v[20:21], v[158:159], v[20:21], v[38:39]
	s_cbranch_vccnz .LBB0_1427
	global_store_dwordx4 v[36:37], v[22:25], off offset:512
	global_store_dwordx4 v[36:37], v[18:21], off offset:528
	s_cbranch_execnz .LBB0_1401

.LBB0_1403:
	s_or_b64 exec, exec, s[26:27]
	v_lshlrev_b32_e32 v20, 16, v70
	v_and_b32_e32 v21, 0xffff0000, v70
	v_pk_fma_f32 v[14:15], v[158:159], v[14:15], v[20:21]
	v_lshlrev_b32_e32 v20, 16, v71
	v_and_b32_e32 v21, 0xffff0000, v71
	v_lshlrev_b64 v[22:23], 10, v[94:95]
	v_pk_fma_f32 v[16:17], v[158:159], v[16:17], v[20:21]
	v_lshlrev_b32_e32 v20, 16, v72
	v_and_b32_e32 v21, 0xffff0000, v72
	s_waitcnt lgkmcnt(0)
	v_lshl_add_u64 v[18:19], v[22:23], 0, v[180:181]
	v_pk_fma_f32 v[10:11], v[158:159], v[10:11], v[20:21]
	v_lshlrev_b32_e32 v20, 16, v73
	v_and_b32_e32 v21, 0xffff0000, v73
	v_pk_fma_f32 v[12:13], v[158:159], v[12:13], v[20:21]
	s_and_b64 vcc, exec, s[6:7]
	v_lshl_add_u64 v[20:21], v[18:19], 2, s[2:3]
	s_cbranch_vccnz .LBB0_1428
	global_store_dwordx4 v[20:21], v[14:17], off
	global_store_dwordx4 v[20:21], v[10:13], off offset:16
	s_cbranch_execnz .LBB0_1406

.LBB0_1406:
	v_lshlrev_b32_e32 v22, 16, v66
	v_and_b32_e32 v23, 0xffff0000, v66
	v_pk_fma_f32 v[6:7], v[158:159], v[6:7], v[22:23]
	v_lshlrev_b32_e32 v22, 16, v67
	v_and_b32_e32 v23, 0xffff0000, v67
	v_pk_fma_f32 v[8:9], v[158:159], v[8:9], v[22:23]
	v_lshlrev_b32_e32 v22, 16, v68
	v_and_b32_e32 v23, 0xffff0000, v68
	v_pk_fma_f32 v[2:3], v[158:159], v[2:3], v[22:23]
	v_lshlrev_b32_e32 v22, 16, v69
	v_and_b32_e32 v23, 0xffff0000, v69
	s_and_b64 vcc, exec, s[6:7]
	v_pk_fma_f32 v[4:5], v[158:159], v[4:5], v[22:23]
	s_cbranch_vccnz .LBB0_1429
	global_store_dwordx4 v[20:21], v[6:9], off offset:512
	global_store_dwordx4 v[20:21], v[2:5], off offset:528
	s_cbranch_execnz .LBB0_1409
